# group barriers extended to seam 5 (s5_norm rows panel-local); stagger moved to s5_norm start
# speedup vs baseline: 1.0183x; 1.0021x over previous
.LBB0_997:
	s_cmp_lt_i32 s24, 6
	s_cselect_b64 s[0:1], -1, 0
	s_and_b64 s[6:7], s[0:1], s[6:7]
	s_andn2_b64 vcc, exec, s[6:7]
	v_lshrrev_b32_e32 v145, 4, v144
	s_cbranch_vccnz .LBB0_1002
	s_add_u32 s8, s22, 0x1be4c100
	s_addc_u32 s9, s23, 0
	v_and_b32_e32 v0, 63, v144
	global_load_ubyte v1, v0, s[8:9] sc1
	global_load_ubyte v2, v0, s[8:9] offset:64 sc1
	global_load_ubyte v3, v0, s[8:9] offset:128 sc1
	global_load_ubyte v4, v0, s[8:9] offset:192 sc1
	s_waitcnt vmcnt(0)
	v_cmp_eq_u32_e32 vcc, v1, v2
	v_cmp_eq_u32_e64 s[10:11], v1, v3
	v_cmp_eq_u32_e64 s[12:13], v1, v4
	s_nop 3
	s_and_b64 s[10:11], s[10:11], s[12:13]
	s_and_b64 vcc, vcc, s[10:11]
	s_cmp_eq_u64 vcc, exec
	s_cselect_b32 s32, 1, 0
	s_cmp_eq_u32 s32, 0
	s_cbranch_scc1 .Lstag_done
	s_and_b32 s98, s3, 3
	s_cmp_eq_u32 s98, 0
	s_cbranch_scc1 .Lstag_done

.Lstag_done:
	s_waitcnt vmcnt(0)
	v_and_b32_e32 v0, 60, v145
	s_and_b32 s98, s3, 7
	s_lshl_b32 s98, s98, 11
	s_bfe_u32 s99, s3, 0x30003
	s_lshl_b32 s99, s99, 8
	s_or_b32 s98, s98, s99
	s_lshr_b32 s99, s3, 6
	s_lshl_b32 s99, s99, 6
	s_or_b32 s98, s98, s99
	v_add_u32_e32 v0, s98, v0
	s_movk_i32 s0, 0x4000
	v_cmp_gt_i32_e32 vcc, s0, v0
	s_and_saveexec_b64 s[8:9], vcc
	s_cbranch_execz .LBB0_1001
	v_lshlrev_b32_e32 v1, 4, v144
	v_and_b32_e32 v1, 0x3f0, v1
	s_waitcnt lgkmcnt(0)
	v_readlane_b32 s36, v248, 24
	v_lshlrev_b32_e32 v4, 2, v1
	v_mov_b32_e32 v5, 0
	v_readlane_b32 s44, v248, 32
	v_readlane_b32 s45, v248, 33
	s_mov_b64 s[0:1], 0x5e00000
	s_lshl_b32 s2, s26, 5
	v_lshl_add_u64 v[2:3], s[44:45], 0, v[4:5]
	v_lshlrev_b32_e32 v4, 1, v1
	v_mbcnt_lo_u32_b32 v1, -1, 0
	v_mbcnt_hi_u32_b32 v1, -1, v1
	v_and_b32_e32 v6, 64, v1
	v_add_u32_e32 v6, 64, v6
	v_xor_b32_e32 v7, 32, v1
	v_cmp_lt_i32_e32 vcc, v7, v6
	v_lshl_add_u64 v[4:5], s[22:23], 0, v[4:5]
	v_lshl_add_u64 v[4:5], v[4:5], 0, s[0:1]
	v_cndmask_b32_e32 v7, v1, v7, vcc
	v_lshlrev_b32_e32 v30, 2, v7
	v_xor_b32_e32 v7, 16, v1
	v_cmp_lt_i32_e32 vcc, v7, v6
	s_mov_b32 s0, 0x358637bd
	s_mov_b64 s[10:11], 0
	v_cndmask_b32_e32 v7, v1, v7, vcc
	v_lshlrev_b32_e32 v31, 2, v7
	v_xor_b32_e32 v7, 8, v1
	v_cmp_lt_i32_e32 vcc, v7, v6
	s_mov_b32 s12, 0x3a800000
	s_mov_b32 s13, 0x800000
	v_cndmask_b32_e32 v7, v1, v7, vcc
	v_lshlrev_b32_e32 v32, 2, v7
	v_xor_b32_e32 v7, 4, v1
	v_cmp_lt_i32_e32 vcc, v7, v6
	s_movk_i32 s14, 0x3fff
	v_readlane_b32 s37, v248, 25
	v_cndmask_b32_e32 v7, v1, v7, vcc
	v_lshlrev_b32_e32 v33, 2, v7
	v_xor_b32_e32 v7, 2, v1
	v_cmp_lt_i32_e32 vcc, v7, v6
	v_readlane_b32 s38, v248, 26
	v_readlane_b32 s39, v248, 27
	v_cndmask_b32_e32 v7, v1, v7, vcc
	v_lshlrev_b32_e32 v34, 2, v7
	v_xor_b32_e32 v7, 1, v1
	v_cmp_lt_i32_e32 vcc, v7, v6
	v_readlane_b32 s40, v248, 28
	v_readlane_b32 s41, v248, 29
	v_cndmask_b32_e32 v1, v1, v7, vcc
	v_lshlrev_b32_e32 v35, 2, v1
	v_mov_b64_e32 v[6:7], s[0:1]
	v_readlane_b32 s42, v248, 30
	v_readlane_b32 s43, v248, 31
	v_readlane_b32 s46, v248, 34
	v_readlane_b32 s47, v248, 35
	v_readlane_b32 s48, v248, 36
	v_readlane_b32 s49, v248, 37
	v_readlane_b32 s50, v248, 38
	v_readlane_b32 s51, v248, 39
	global_load_dwordx4 v[180:183], v[2:3], off
	global_load_dwordx4 v[184:187], v[2:3], off offset:16
	global_load_dwordx4 v[188:191], v[2:3], off offset:32
	global_load_dwordx4 v[192:195], v[2:3], off offset:48
.LBB0_1000:
	v_ashrrev_i32_e32 v1, 31, v0
	v_lshlrev_b64 v[8:9], 12, v[0:1]
	v_lshl_add_u64 v[10:11], v[4:5], 0, v[8:9]
	global_load_dwordx4 v[12:15], v[10:11], off offset:16
	global_load_dwordx4 v[16:19], v[10:11], off
	v_add_u32_e32 v8, 1, v0
	v_ashrrev_i32_e32 v9, 31, v8
	v_lshlrev_b64 v[8:9], 12, v[8:9]
	v_lshl_add_u64 v[8:9], v[4:5], 0, v[8:9]
	global_load_dwordx4 v[22:25], v[8:9], off offset:16
	global_load_dwordx4 v[36:39], v[8:9], off
	global_load_dwordx4 v[40:43], v[2:3], off offset:48
	global_load_dwordx4 v[44:47], v[2:3], off offset:32
	global_load_dwordx4 v[48:51], v[2:3], off offset:16
	global_load_dwordx4 v[52:55], v[2:3], off
	s_waitcnt vmcnt(7)
	v_lshlrev_b32_e32 v56, 16, v15
	v_and_b32_e32 v57, 0xffff0000, v15
	v_lshlrev_b32_e32 v58, 16, v14
	v_and_b32_e32 v59, 0xffff0000, v14
	s_waitcnt vmcnt(6)
	v_lshlrev_b32_e32 v64, 16, v19
	v_and_b32_e32 v65, 0xffff0000, v19
	v_lshlrev_b32_e32 v66, 16, v18
	v_and_b32_e32 v67, 0xffff0000, v18
	v_and_b32_e32 v69, 0xffff0000, v17
	s_waitcnt vmcnt(5)
	v_lshlrev_b32_e32 v14, 16, v25
	v_and_b32_e32 v15, 0xffff0000, v25
	v_lshlrev_b32_e32 v18, 16, v23
	v_and_b32_e32 v19, 0xffff0000, v23
	s_waitcnt vmcnt(4)
	v_and_b32_e32 v23, 0xffff0000, v39
	v_and_b32_e32 v25, 0xffff0000, v38
	v_and_b32_e32 v27, 0xffff0000, v37
	v_lshlrev_b32_e32 v68, 16, v17
	v_lshlrev_b32_e32 v70, 16, v16
	v_and_b32_e32 v71, 0xffff0000, v16
	v_lshlrev_b32_e32 v16, 16, v24
	v_and_b32_e32 v17, 0xffff0000, v24
	v_lshlrev_b32_e32 v20, 16, v22
	v_and_b32_e32 v21, 0xffff0000, v22
	v_lshlrev_b32_e32 v22, 16, v39
	v_lshlrev_b32_e32 v24, 16, v38
	v_lshlrev_b32_e32 v26, 16, v37
	v_mov_b32_e32 v39, v65
	v_mov_b32_e32 v81, v67
	v_mov_b32_e32 v85, v69
	v_mov_b32_e32 v38, v23
	v_mov_b32_e32 v80, v25
	v_mov_b32_e32 v84, v27
	v_lshlrev_b32_e32 v28, 16, v36
	v_and_b32_e32 v29, 0xffff0000, v36
	v_mov_b32_e32 v37, v64
	v_mov_b32_e32 v79, v66
	v_mov_b32_e32 v83, v68
	v_mov_b32_e32 v36, v22
	v_mov_b32_e32 v78, v24
	v_mov_b32_e32 v82, v26
	v_pk_mul_f32 v[38:39], v[38:39], v[38:39]
	v_pk_mul_f32 v[80:81], v[80:81], v[80:81]
	v_pk_mul_f32 v[84:85], v[84:85], v[84:85]
	v_and_b32_e32 v61, 0xffff0000, v13
	v_and_b32_e32 v63, 0xffff0000, v12
	v_pk_fma_f32 v[36:37], v[36:37], v[36:37], v[38:39]
	v_pk_fma_f32 v[38:39], v[78:79], v[78:79], v[80:81]
	v_pk_fma_f32 v[78:79], v[82:83], v[82:83], v[84:85]
	v_mov_b32_e32 v82, v29
	v_mov_b32_e32 v83, v71
	v_lshlrev_b32_e32 v60, 16, v13
	v_lshlrev_b32_e32 v62, 16, v12
	v_mov_b32_e32 v72, v57
	v_mov_b32_e32 v73, v59
	v_mov_b32_e32 v76, v61
	v_mov_b32_e32 v77, v63
	v_mov_b32_e32 v80, v28
	v_mov_b32_e32 v81, v70
	v_pk_mul_f32 v[82:83], v[82:83], v[82:83]
	v_mov_b32_e32 v12, v56
	v_mov_b32_e32 v13, v58
	v_mov_b32_e32 v74, v60
	v_mov_b32_e32 v75, v62
	v_pk_mul_f32 v[72:73], v[72:73], v[72:73]
	v_pk_mul_f32 v[76:77], v[76:77], v[76:77]
	v_mov_b32_e32 v92, v19
	v_mov_b32_e32 v93, v21
	v_pk_fma_f32 v[80:81], v[80:81], v[80:81], v[82:83]
	v_mov_b32_e32 v90, v18
	v_mov_b32_e32 v91, v20
	v_pk_fma_f32 v[12:13], v[12:13], v[12:13], v[72:73]
	v_pk_fma_f32 v[72:73], v[74:75], v[74:75], v[76:77]
	v_pk_mul_f32 v[76:77], v[92:93], v[92:93]
	v_pk_add_f32 v[78:79], v[80:81], v[78:79]
	v_mov_b32_e32 v88, v15
	v_mov_b32_e32 v89, v17
	v_pk_fma_f32 v[76:77], v[90:91], v[90:91], v[76:77]
	v_pk_add_f32 v[38:39], v[38:39], v[78:79]
	v_mov_b32_e32 v86, v14
	v_mov_b32_e32 v87, v16
	v_pk_mul_f32 v[74:75], v[88:89], v[88:89]
	v_pk_add_f32 v[36:37], v[36:37], v[38:39]
	v_mov_b32_e32 v38, v77
	v_mov_b32_e32 v39, v73
	v_pk_fma_f32 v[74:75], v[86:87], v[86:87], v[74:75]
	v_pk_add_f32 v[36:37], v[38:39], v[36:37]
	v_mov_b32_e32 v77, v72
	v_pk_add_f32 v[36:37], v[76:77], v[36:37]
	v_mov_b32_e32 v38, v75
	v_mov_b32_e32 v39, v13
	v_pk_add_f32 v[36:37], v[38:39], v[36:37]
	v_mov_b32_e32 v75, v12
	v_pk_add_f32 v[12:13], v[74:75], v[36:37]
	ds_bpermute_b32 v37, v30, v13
	ds_bpermute_b32 v36, v30, v12
	s_waitcnt lgkmcnt(0)
	v_pk_add_f32 v[12:13], v[12:13], v[36:37]
	ds_bpermute_b32 v37, v31, v13
	ds_bpermute_b32 v36, v31, v12
	s_waitcnt lgkmcnt(0)
	v_pk_add_f32 v[12:13], v[12:13], v[36:37]
	ds_bpermute_b32 v37, v32, v13
	ds_bpermute_b32 v36, v32, v12
	s_waitcnt lgkmcnt(0)
	v_pk_add_f32 v[12:13], v[12:13], v[36:37]
	ds_bpermute_b32 v37, v33, v13
	ds_bpermute_b32 v36, v33, v12
	s_waitcnt lgkmcnt(0)
	v_pk_add_f32 v[12:13], v[12:13], v[36:37]
	ds_bpermute_b32 v37, v34, v13
	ds_bpermute_b32 v36, v34, v12
	s_waitcnt lgkmcnt(0)
	v_pk_add_f32 v[36:37], v[12:13], v[36:37]
	ds_bpermute_b32 v39, v35, v37
	ds_bpermute_b32 v38, v35, v36
	v_add_u32_e32 v12, 2, v0
	v_ashrrev_i32_e32 v13, 31, v12
	v_lshlrev_b64 v[12:13], 12, v[12:13]
	v_lshl_add_u64 v[12:13], v[4:5], 0, v[12:13]
	s_waitcnt lgkmcnt(0)
	v_pk_add_f32 v[36:37], v[36:37], v[38:39]
	s_nop 0
	v_pk_fma_f32 v[72:73], v[36:37], s[12:13], v[6:7] op_sel_hi:[1,0,0]
	global_load_dwordx4 v[36:39], v[12:13], off offset:16
	v_mul_f32_e32 v1, 0x4b800000, v73
	v_cmp_gt_f32_e32 vcc, s13, v73
	s_nop 1
	v_cndmask_b32_e32 v1, v73, v1, vcc
	v_rsq_f32_e32 v1, v1
	s_nop 0
	v_mul_f32_e32 v73, 0x45800000, v1
	v_cndmask_b32_e32 v74, v1, v73, vcc
	v_pk_mul_f32 v[70:71], v[74:75], v[70:71] op_sel_hi:[0,1]
	v_pk_mul_f32 v[68:69], v[74:75], v[68:69] op_sel_hi:[0,1]
	s_waitcnt vmcnt(1)
	v_pk_mul_f32 v[52:53], v[52:53], v[70:71]
	v_pk_mul_f32 v[54:55], v[54:55], v[68:69]
	v_cvt_pk_bf16_f32 v52, v52, v53
	v_cvt_pk_bf16_f32 v53, v54, v55
	v_pk_mul_f32 v[54:55], v[74:75], v[66:67] op_sel_hi:[0,1]
	v_pk_mul_f32 v[48:49], v[48:49], v[54:55]
	v_mul_f32_e32 v1, 0x4b800000, v72
	v_cvt_pk_bf16_f32 v54, v48, v49
	v_pk_mul_f32 v[48:49], v[74:75], v[64:65] op_sel_hi:[0,1]
	v_pk_mul_f32 v[48:49], v[50:51], v[48:49]
	v_cmp_gt_f32_e32 vcc, s13, v72
	v_cvt_pk_bf16_f32 v55, v48, v49
	v_pk_mul_f32 v[48:49], v[74:75], v[62:63] op_sel_hi:[0,1]
	v_pk_mul_f32 v[44:45], v[44:45], v[48:49]
	v_pk_mul_f32 v[48:49], v[74:75], v[60:61] op_sel_hi:[0,1]
	v_pk_mul_f32 v[46:47], v[46:47], v[48:49]
	v_cvt_pk_bf16_f32 v44, v44, v45
	v_cvt_pk_bf16_f32 v45, v46, v47
	v_pk_mul_f32 v[46:47], v[74:75], v[58:59] op_sel_hi:[0,1]
	v_pk_mul_f32 v[40:41], v[46:47], v[40:41]
	v_cndmask_b32_e32 v1, v72, v1, vcc
	v_cvt_pk_bf16_f32 v46, v40, v41
	v_pk_mul_f32 v[40:41], v[74:75], v[56:57] op_sel_hi:[0,1]
	v_pk_mul_f32 v[40:41], v[40:41], v[42:43]
	v_rsq_f32_e32 v1, v1
	v_cvt_pk_bf16_f32 v47, v40, v41
	global_store_dwordx4 v[10:11], v[52:55], off
	global_store_dwordx4 v[10:11], v[44:47], off offset:16
	s_nop 0
	global_load_dwordx4 v[56:59], v[12:13], off
	v_add_u32_e32 v10, 3, v0
	v_ashrrev_i32_e32 v11, 31, v10
	v_lshlrev_b64 v[10:11], 12, v[10:11]
	v_lshl_add_u64 v[10:11], v[4:5], 0, v[10:11]
	global_load_dwordx4 v[60:63], v[10:11], off offset:16
	global_load_dwordx4 v[64:67], v[10:11], off
	v_mul_f32_e32 v73, 0x45800000, v1
	v_add_u32_e32 v0, 32, v0
	v_and_b32_e32 v247, 32, v0
	v_cmp_eq_u32_e64 s[0:1], 0, v247
	s_or_b64 s[10:11], s[0:1], s[10:11]
	s_waitcnt vmcnt(5)
	v_and_b32_e32 v69, 0xffff0000, v39
	v_and_b32_e32 v71, 0xffff0000, v38
	v_lshlrev_b32_e32 v68, 16, v39
	v_lshlrev_b32_e32 v70, 16, v38
	v_mov_b32_e32 v76, v69
	v_mov_b32_e32 v77, v71
	v_lshlrev_b32_e32 v38, 16, v37
	v_and_b32_e32 v39, 0xffff0000, v37
	v_lshlrev_b32_e32 v74, 16, v36
	v_and_b32_e32 v75, 0xffff0000, v36
	v_mov_b32_e32 v36, v68
	v_mov_b32_e32 v37, v70
	v_pk_mul_f32 v[76:77], v[76:77], v[76:77]
	v_mov_b32_e32 v72, v39
	v_pk_fma_f32 v[36:37], v[36:37], v[36:37], v[76:77]
	v_cndmask_b32_e32 v76, v1, v73, vcc
	v_pk_mul_f32 v[28:29], v[76:77], v[28:29] op_sel_hi:[0, 1]
	v_pk_mul_f32 v[26:27], v[76:77], v[26:27] op_sel_hi:[0, 1]
	v_pk_mul_f32 v[24:25], v[76:77], v[24:25] op_sel_hi:[0, 1]
	v_pk_mul_f32 v[22:23], v[76:77], v[22:23] op_sel_hi:[0, 1]
	v_pk_mul_f32 v[20:21], v[76:77], v[20:21] op_sel_hi:[0, 1]
	v_pk_mul_f32 v[18:19], v[76:77], v[18:19] op_sel_hi:[0, 1]
	v_pk_mul_f32 v[16:17], v[76:77], v[16:17] op_sel_hi:[0, 1]
	v_pk_mul_f32 v[14:15], v[76:77], v[14:15] op_sel_hi:[0, 1]
	v_mov_b32_e32 v73, v75
	v_mov_b32_e32 v78, v38
	v_mov_b32_e32 v79, v74
	s_waitcnt vmcnt(5)
	v_pk_mul_f32 v[28:29], v[180:181], v[28:29]
	v_pk_mul_f32 v[26:27], v[182:183], v[26:27]
	s_waitcnt vmcnt(5)
	v_pk_mul_f32 v[24:25], v[184:185], v[24:25]
	v_pk_mul_f32 v[22:23], v[186:187], v[22:23]
	s_waitcnt vmcnt(5)
	v_pk_mul_f32 v[20:21], v[188:189], v[20:21]
	v_pk_mul_f32 v[40:41], v[18:19], v[190:191]
	s_waitcnt vmcnt(5)
	v_pk_mul_f32 v[42:43], v[16:17], v[192:193]
	v_pk_mul_f32 v[44:45], v[14:15], v[194:195]
	v_cvt_pk_bf16_f32 v14, v28, v29
	v_cvt_pk_bf16_f32 v15, v26, v27
	v_cvt_pk_bf16_f32 v16, v24, v25
	v_cvt_pk_bf16_f32 v17, v22, v23
	v_cvt_pk_bf16_f32 v18, v20, v21
	v_cvt_pk_bf16_f32 v19, v40, v41
	v_cvt_pk_bf16_f32 v20, v42, v43
	v_cvt_pk_bf16_f32 v21, v44, v45
	global_store_dwordx4 v[8:9], v[14:17], off
	global_store_dwordx4 v[8:9], v[18:21], off offset:16
	s_nop 0
	s_waitcnt vmcnt(3)
	v_and_b32_e32 v49, 0xffff0000, v63
	v_and_b32_e32 v51, 0xffff0000, v62
	v_lshlrev_b32_e32 v48, 16, v63
	v_lshlrev_b32_e32 v50, 16, v62
	v_mov_b32_e32 v54, v49
	v_mov_b32_e32 v55, v51
	v_mov_b32_e32 v52, v48
	v_mov_b32_e32 v53, v50
	v_pk_mul_f32 v[54:55], v[54:55], v[54:55]
	v_lshlrev_b32_e32 v44, 16, v57
	v_and_b32_e32 v45, 0xffff0000, v57
	v_pk_fma_f32 v[52:53], v[52:53], v[52:53], v[54:55]
	v_and_b32_e32 v55, 0xffff0000, v61
	v_and_b32_e32 v57, 0xffff0000, v60
	v_lshlrev_b32_e32 v46, 16, v56
	v_and_b32_e32 v47, 0xffff0000, v56
	v_lshlrev_b32_e32 v54, 16, v61
	v_lshlrev_b32_e32 v56, 16, v60
	v_mov_b32_e32 v60, v55
	v_mov_b32_e32 v61, v57
	v_lshlrev_b32_e32 v40, 16, v59
	v_and_b32_e32 v41, 0xffff0000, v59
	v_lshlrev_b32_e32 v42, 16, v58
	v_and_b32_e32 v43, 0xffff0000, v58
	v_mov_b32_e32 v58, v54
	v_mov_b32_e32 v59, v56
	v_pk_mul_f32 v[60:61], v[60:61], v[60:61]
	v_pk_mul_f32 v[8:9], v[72:73], v[72:73]
	v_pk_fma_f32 v[58:59], v[58:59], v[58:59], v[60:61]
	s_waitcnt vmcnt(2)
	v_and_b32_e32 v61, 0xffff0000, v67
	v_lshlrev_b32_e32 v60, 16, v67
	v_and_b32_e32 v63, 0xffff0000, v66
	v_mov_b32_e32 v76, v61
	v_mov_b32_e32 v77, v41
	v_pk_fma_f32 v[8:9], v[78:79], v[78:79], v[8:9]
	v_lshlrev_b32_e32 v62, 16, v66
	v_lshlrev_b32_e32 v66, 16, v65
	v_and_b32_e32 v67, 0xffff0000, v65
	v_lshlrev_b32_e32 v72, 16, v64
	v_and_b32_e32 v73, 0xffff0000, v64
	v_mov_b32_e32 v64, v60
	v_mov_b32_e32 v65, v40
	v_pk_mul_f32 v[76:77], v[76:77], v[76:77]
	v_mov_b32_e32 v78, v63
	v_mov_b32_e32 v79, v43
	v_pk_fma_f32 v[64:65], v[64:65], v[64:65], v[76:77]
	v_mov_b32_e32 v76, v62
	v_mov_b32_e32 v77, v42
	v_pk_mul_f32 v[78:79], v[78:79], v[78:79]
	v_mov_b32_e32 v80, v67
	v_mov_b32_e32 v81, v45
	v_pk_fma_f32 v[76:77], v[76:77], v[76:77], v[78:79]
	v_mov_b32_e32 v78, v66
	v_mov_b32_e32 v79, v44
	v_pk_mul_f32 v[80:81], v[80:81], v[80:81]
	v_mov_b32_e32 v82, v73
	v_mov_b32_e32 v83, v47
	v_pk_fma_f32 v[78:79], v[78:79], v[78:79], v[80:81]
	v_mov_b32_e32 v80, v72
	v_mov_b32_e32 v81, v46
	v_pk_mul_f32 v[82:83], v[82:83], v[82:83]
	s_nop 0
	v_pk_fma_f32 v[80:81], v[80:81], v[80:81], v[82:83]
	s_nop 0
	v_pk_add_f32 v[78:79], v[80:81], v[78:79]
	s_nop 0
	v_pk_add_f32 v[76:77], v[76:77], v[78:79]
	s_nop 0
	v_pk_add_f32 v[64:65], v[64:65], v[76:77]
	v_mov_b32_e32 v76, v59
	v_mov_b32_e32 v77, v9
	v_pk_add_f32 v[64:65], v[76:77], v[64:65]
	v_mov_b32_e32 v59, v8
	v_pk_add_f32 v[8:9], v[58:59], v[64:65]
	v_mov_b32_e32 v58, v53
	v_mov_b32_e32 v59, v37
	v_pk_add_f32 v[8:9], v[58:59], v[8:9]
	v_mov_b32_e32 v53, v36
	v_pk_add_f32 v[8:9], v[52:53], v[8:9]
	ds_bpermute_b32 v37, v30, v9
	ds_bpermute_b32 v36, v30, v8
	s_waitcnt lgkmcnt(0)
	v_pk_add_f32 v[8:9], v[8:9], v[36:37]
	ds_bpermute_b32 v37, v31, v9
	ds_bpermute_b32 v36, v31, v8
	s_waitcnt lgkmcnt(0)
	v_pk_add_f32 v[8:9], v[8:9], v[36:37]
	ds_bpermute_b32 v37, v32, v9
	ds_bpermute_b32 v36, v32, v8
	s_waitcnt lgkmcnt(0)
	v_pk_add_f32 v[8:9], v[8:9], v[36:37]
	ds_bpermute_b32 v37, v33, v9
	ds_bpermute_b32 v36, v33, v8
	s_waitcnt lgkmcnt(0)
	v_pk_add_f32 v[8:9], v[8:9], v[36:37]
	ds_bpermute_b32 v37, v34, v9
	ds_bpermute_b32 v36, v34, v8
	s_waitcnt lgkmcnt(0)
	v_pk_add_f32 v[8:9], v[8:9], v[36:37]
	ds_bpermute_b32 v37, v35, v9
	ds_bpermute_b32 v36, v35, v8
	s_waitcnt lgkmcnt(0)
	v_pk_add_f32 v[8:9], v[8:9], v[36:37]
	s_nop 0
	v_pk_fma_f32 v[8:9], v[8:9], s[12:13], v[6:7] op_sel_hi:[1, 0, 0]
	s_nop 0
	v_mul_f32_e32 v1, 0x4b800000, v9
	v_cmp_gt_f32_e32 vcc, s13, v9
	s_nop 1
	v_cndmask_b32_e32 v1, v9, v1, vcc
	v_rsq_f32_e32 v1, v1
	s_nop 0
	v_mul_f32_e32 v9, 0x45800000, v1
	v_cndmask_b32_e32 v36, v1, v9, vcc
	v_pk_mul_f32 v[46:47], v[36:37], v[46:47] op_sel_hi:[0, 1]
	v_pk_mul_f32 v[44:45], v[36:37], v[44:45] op_sel_hi:[0, 1]
	s_waitcnt vmcnt(2)
	v_pk_mul_f32 v[26:27], v[180:181], v[46:47]
	v_pk_mul_f32 v[28:29], v[182:183], v[44:45]
	v_cvt_pk_bf16_f32 v26, v26, v27
	v_cvt_pk_bf16_f32 v27, v28, v29
	v_pk_mul_f32 v[28:29], v[36:37], v[42:43] op_sel_hi:[0, 1]
	v_pk_mul_f32 v[22:23], v[184:185], v[28:29]
	v_mul_f32_e32 v1, 0x4b800000, v8
	v_cvt_pk_bf16_f32 v28, v22, v23
	v_pk_mul_f32 v[22:23], v[36:37], v[40:41] op_sel_hi:[0, 1]
	v_pk_mul_f32 v[22:23], v[186:187], v[22:23]
	v_cmp_gt_f32_e32 vcc, s13, v8
	v_cvt_pk_bf16_f32 v29, v22, v23
	v_pk_mul_f32 v[22:23], v[36:37], v[74:75] op_sel_hi:[0, 1]
	v_pk_mul_f32 v[18:19], v[188:189], v[22:23]
	v_pk_mul_f32 v[22:23], v[36:37], v[38:39] op_sel_hi:[0, 1]
	v_pk_mul_f32 v[20:21], v[22:23], v[190:191]
	v_cvt_pk_bf16_f32 v18, v18, v19
	v_cvt_pk_bf16_f32 v19, v20, v21
	v_pk_mul_f32 v[20:21], v[36:37], v[70:71] op_sel_hi:[0, 1]
	v_pk_mul_f32 v[14:15], v[20:21], v[192:193]
	v_cndmask_b32_e32 v1, v8, v1, vcc
	v_cvt_pk_bf16_f32 v20, v14, v15
	v_pk_mul_f32 v[14:15], v[36:37], v[68:69] op_sel_hi:[0, 1]
	v_pk_mul_f32 v[14:15], v[14:15], v[194:195]
	v_rsq_f32_e32 v1, v1
	v_cvt_pk_bf16_f32 v21, v14, v15
	global_store_dwordx4 v[12:13], v[26:29], off
	global_store_dwordx4 v[12:13], v[18:21], off offset:16
	s_nop 0
	v_mul_f32_e32 v8, 0x45800000, v1
	v_cndmask_b32_e32 v8, v1, v8, vcc
	v_pk_mul_f32 v[28:29], v[8:9], v[72:73] op_sel_hi:[0, 1]
	v_pk_mul_f32 v[36:37], v[8:9], v[66:67] op_sel_hi:[0, 1]
	v_pk_mul_f32 v[38:39], v[8:9], v[62:63] op_sel_hi:[0, 1]
	v_pk_mul_f32 v[40:41], v[8:9], v[60:61] op_sel_hi:[0, 1]
	v_pk_mul_f32 v[42:43], v[8:9], v[56:57] op_sel_hi:[0, 1]
	v_pk_mul_f32 v[44:45], v[8:9], v[54:55] op_sel_hi:[0, 1]
	v_pk_mul_f32 v[46:47], v[8:9], v[50:51] op_sel_hi:[0, 1]
	v_pk_mul_f32 v[8:9], v[8:9], v[48:49] op_sel_hi:[0, 1]
	s_waitcnt vmcnt(4)
	v_pk_mul_f32 v[12:13], v[180:181], v[28:29]
	v_pk_mul_f32 v[14:15], v[182:183], v[36:37]
	s_waitcnt vmcnt(4)
	v_pk_mul_f32 v[16:17], v[184:185], v[38:39]
	v_pk_mul_f32 v[18:19], v[186:187], v[40:41]
	s_waitcnt vmcnt(4)
	v_pk_mul_f32 v[20:21], v[188:189], v[42:43]
	v_pk_mul_f32 v[22:23], v[44:45], v[190:191]
	s_waitcnt vmcnt(4)
	v_pk_mul_f32 v[24:25], v[46:47], v[192:193]
	v_pk_mul_f32 v[8:9], v[8:9], v[194:195]
	v_cvt_pk_bf16_f32 v12, v12, v13
	v_cvt_pk_bf16_f32 v13, v14, v15
	v_cvt_pk_bf16_f32 v14, v16, v17
	v_cvt_pk_bf16_f32 v15, v18, v19
	v_cvt_pk_bf16_f32 v16, v20, v21
	v_cvt_pk_bf16_f32 v17, v22, v23
	v_cvt_pk_bf16_f32 v18, v24, v25
	v_cvt_pk_bf16_f32 v19, v8, v9
	global_store_dwordx4 v[10:11], v[12:15], off
	global_store_dwordx4 v[10:11], v[16:19], off offset:16
	s_andn2_b64 exec, exec, s[10:11]
	s_cbranch_execnz .LBB0_1000

.LBB0_1002:
	s_cmp_gt_i32 s25, 6
	s_cselect_b64 s[0:1], -1, 0
	s_and_b64 s[6:7], s[6:7], s[0:1]
	s_andn2_b64 vcc, exec, s[6:7]
	s_cbranch_vccnz .LBB0_1056
	s_cmp_lg_u32 s32, 0
	s_addc_u32 s32, s32, 0
	s_waitcnt vmcnt(0)
	s_waitcnt vmcnt(0) lgkmcnt(0)
	s_barrier
	s_and_saveexec_b64 s[6:7], s[4:5]
	s_cbranch_execz .LBB0_1055
	s_cmp_lg_u32 s32, 0
	s_cbranch_scc1 .Lgb5
	s_add_i32 s2, 0, 0x23fe0
	v_mov_b32_e32 v0, s2
	s_waitcnt vmcnt(0) expcnt(0) lgkmcnt(0)
	ds_read_b32 v2, v0
	s_add_i32 s2, 0, 0x23fe4
	v_mov_b32_e32 v0, s2
	ds_read_b32 v0, v0
	s_waitcnt lgkmcnt(1)
	v_cmp_ne_u32_e32 vcc, 0, v2
	s_cbranch_vccnz .LBB0_1019
	s_add_u32 s8, s22, 0x1be4c300
	s_addc_u32 s9, s23, 0
	s_add_u32 s10, s22, 0x1be4c500
	s_addc_u32 s11, s23, 0
	s_add_u32 s12, s22, 0x1be4c600
	s_addc_u32 s13, s23, 0
	s_add_u32 s14, s22, 0x1be4c700
	s_addc_u32 s15, s23, 0
	s_add_u32 s16, s22, 0x1be4c800
	s_addc_u32 s17, s23, 0
	s_add_u32 s18, s22, 0x1be4c900
	s_addc_u32 s19, s23, 0
	s_add_u32 s30, s22, 0x1be4ca00
	s_addc_u32 s31, s23, 0
	s_add_u32 s34, s22, 0x1be4cb00
	s_addc_u32 s35, s23, 0
	s_add_u32 s36, s22, 0x1be4cc00
	s_addc_u32 s37, s23, 0
	s_add_u32 s38, s22, 0x1be4cd00
	s_addc_u32 s39, s23, 0
	s_add_u32 s40, s22, 0x1be4ce00
	s_addc_u32 s41, s23, 0
	s_add_u32 s42, s22, 0x1be4cf00
	s_addc_u32 s43, s23, 0
	s_add_u32 s44, s22, 0x1be4d000
	s_addc_u32 s45, s23, 0
	s_add_u32 s46, s22, 0x1be4d100
	s_addc_u32 s47, s23, 0
	s_add_u32 s48, s22, 0x1be4d200
	s_addc_u32 s49, s23, 0
	s_add_u32 s50, s22, 0x1be4d300
	s_addc_u32 s51, s23, 0
	s_mul_i32 s2, s27, s97
	s_add_u32 s54, s22, 0x1be4d400
	s_mul_i32 s2, s2, s26
	s_addc_u32 s55, s23, 0
	s_mov_b32 s33, 1
	v_mov_b32_e32 v16, 0
	s_branch .LBB0_1007
